# baseline (speedup 1.0000x reference)
.LBB0_186:
	s_or_b64 exec, exec, s[44:45]
	v_lshlrev_b32_e32 v7, 6, v157
	v_mov_b32_e32 v131, v129
	s_waitcnt vmcnt(0)
	v_lshlrev_b32_e32 v21, 2, v157
	v_lshlrev_b32_e32 v22, 13, v6
	v_and_b32_e32 v6, 0x3000, v7
	v_add_u32_e32 v168, 0x18000, v158
	v_lshl_add_u64 v[8:9], s[88:89], 0, v[128:129]
	v_lshl_add_u64 v[16:17], s[2:3], 0, v[128:129]
	v_lshl_add_u64 v[18:19], s[2:3], 0, v[130:131]
	v_and_b32_e32 v20, 0x3c0, v7
	v_and_b32_e32 v21, 32, v21
	v_or_b32_e32 v23, 0x10000, v6
	v_and_b32_e32 v6, 48, v157
	v_readfirstlane_b32 s3, v168
	v_add_u32_e32 v169, 0x1a000, v158
	v_lshl_add_u64 v[10:11], s[88:89], 0, v[130:131]
	v_bitop3_b32 v20, v20, v21, v6 bitop3:0x36
	v_lshl_add_u64 v[6:7], v[8:9], 0, s[72:73]
	s_mov_b32 m0, s3
	v_readfirstlane_b32 s3, v169
	v_add_u32_e32 v170, 0x8000, v158
	v_lshl_add_u64 v[12:13], s[94:95], 0, v[128:129]
	s_waitcnt vmcnt(4)
	s_barrier
	global_load_lds_dwordx4 v[6:7], off
	v_lshl_add_u64 v[6:7], v[10:11], 0, s[72:73]
	s_mov_b32 m0, s3
	v_readfirstlane_b32 s3, v170
	v_add_u32_e32 v171, 0xa000, v158
	v_lshl_add_u64 v[14:15], s[94:95], 0, v[130:131]
	global_load_lds_dwordx4 v[6:7], off
	v_lshl_add_u64 v[6:7], v[12:13], 0, s[72:73]
	s_mov_b32 m0, s3
	v_readfirstlane_b32 s3, v171
	v_add_u32_e32 v172, 0x1c000, v158
	global_load_lds_dwordx4 v[6:7], off
	v_lshl_add_u64 v[6:7], v[14:15], 0, s[72:73]
	s_mov_b32 m0, s3
	v_readfirstlane_b32 s3, v172
	v_add_u32_e32 v173, 0x1e000, v158
	global_load_lds_dwordx4 v[6:7], off
	v_lshl_add_u64 v[6:7], v[16:17], 0, s[72:73]
	s_mov_b32 m0, s3
	v_readfirstlane_b32 s3, v173
	global_load_lds_dwordx4 v[6:7], off
	v_lshl_add_u64 v[6:7], v[18:19], 0, s[72:73]
	s_mov_b32 m0, s3
	s_lshl_b64 s[94:95], s[92:93], 1
	global_load_lds_dwordx4 v[6:7], off
	s_lshr_b64 s[44:45], s[92:93], 31
	s_lshr_b32 s2, s53, 6
	s_mul_i32 s44, s44, s53
	s_mul_hi_u32 s45, s94, s53
	s_xor_b64 s[4:5], s[4:5], -1
	s_add_i32 s3, s2, -2
	s_add_i32 s45, s45, s44
	s_mul_i32 s44, s94, s53
	v_add_u32_e32 v0, v2, v0
	s_add_u32 s44, s42, s44
	v_add_u32_e32 v2, v5, v3
	v_add_lshl_u32 v0, v0, v1, 1
	v_mov_b32_e32 v1, v129
	s_addc_u32 s45, s43, s45
	v_add_lshl_u32 v2, v2, v4, 1
	v_mov_b32_e32 v3, v129
	v_lshl_add_u64 v[132:133], s[44:45], 0, v[0:1]
	v_lshl_add_u64 v[134:135], s[44:45], 0, v[2:3]
	s_mul_i32 s44, s66, s53
	s_mul_hi_u32 s45, s91, s53
	s_add_i32 s45, s45, s44
	s_mul_i32 s44, s91, s53
	s_lshl_b64 s[44:45], s[44:45], 1
	s_add_u32 s44, s34, s44
	s_addc_u32 s45, s35, s45
	v_lshl_add_u64 v[136:137], s[44:45], 0, v[0:1]
	v_lshl_add_u64 v[138:139], s[44:45], 0, v[2:3]
	s_add_u32 s44, s92, 0x80
	s_addc_u32 s45, s93, 0
	s_mul_i32 s45, s45, s53
	s_mul_hi_u32 s69, s44, s53
	s_add_i32 s45, s69, s45
	s_mul_i32 s44, s44, s53
	s_lshl_b64 s[44:45], s[44:45], 1
	s_add_u32 s42, s42, s44
	s_addc_u32 s43, s43, s45
	v_lshl_add_u64 v[140:141], s[42:43], 0, v[0:1]
	v_lshl_add_u64 v[142:143], s[42:43], 0, v[2:3]
	s_add_u32 s42, s91, 0x80
	s_addc_u32 s43, s66, 0
	s_mul_i32 s43, s43, s53
	s_mul_hi_u32 s44, s42, s53
	s_add_i32 s43, s44, s43
	s_mul_i32 s42, s42, s53
	s_lshl_b64 s[42:43], s[42:43], 1
	s_add_u32 s34, s34, s42
	s_waitcnt vmcnt(6)
	s_addc_u32 s35, s35, s43
	v_lshl_add_u64 v[144:145], s[34:35], 0, v[0:1]
	v_mov_b32_e32 v0, 0
	v_lshl_add_u64 v[146:147], s[34:35], 0, v[2:3]
	s_lshl_b32 s44, s53, 8
	s_add_u32 s76, s54, 0x80
	s_addc_u32 s77, s55, 0
	s_sub_u32 s72, s54, s44
	s_subb_u32 s73, s55, 0
	s_add_u32 s72, s72, 0x100
	s_addc_u32 s73, s73, 0
	s_add_u32 s42, s88, 0x100
	s_addc_u32 s43, s89, 0
	s_add_u32 s78, s88, s44
	s_addc_u32 s79, s89, 0
	s_add_u32 s78, s78, 0x100
	s_addc_u32 s79, s79, 0
	s_mov_b32 s34, 0
	v_readfirstlane_b32 s35, v158
	v_add_u32_e32 v174, 0xc000, v158
	v_add_u32_e32 v175, 0xe000, v158
	v_add_u32_e32 v164, v23, v20
	v_add_u32_e32 v162, v22, v20
	v_mov_b32_e32 v1, v0
	v_mov_b32_e32 v2, v0
	v_mov_b32_e32 v3, v0
	v_mov_b32_e32 v4, v0
	v_mov_b32_e32 v5, v0
	v_mov_b32_e32 v6, v0
	v_mov_b32_e32 v7, v0
	v_mov_b32_e32 v8, v0
	v_mov_b32_e32 v9, v0
	v_mov_b32_e32 v10, v0
	v_mov_b32_e32 v11, v0
	v_mov_b32_e32 v12, v0
	v_mov_b32_e32 v13, v0
	v_mov_b32_e32 v14, v0
	v_mov_b32_e32 v15, v0
	v_mov_b32_e32 v16, v0
	v_mov_b32_e32 v17, v0
	v_mov_b32_e32 v18, v0
	v_mov_b32_e32 v19, v0
	v_mov_b32_e32 v20, v0
	v_mov_b32_e32 v21, v0
	v_mov_b32_e32 v22, v0
	v_mov_b32_e32 v23, v0
	v_mov_b32_e32 v24, v0
	v_mov_b32_e32 v25, v0
	v_mov_b32_e32 v26, v0
	v_mov_b32_e32 v27, v0
	v_mov_b32_e32 v28, v0
	v_mov_b32_e32 v29, v0
	v_mov_b32_e32 v30, v0
	v_mov_b32_e32 v31, v0
	v_mov_b32_e32 v32, v0
	v_mov_b32_e32 v33, v0
	v_mov_b32_e32 v34, v0
	v_mov_b32_e32 v35, v0
	v_mov_b32_e32 v36, v0
	v_mov_b32_e32 v37, v0
	v_mov_b32_e32 v38, v0
	v_mov_b32_e32 v39, v0
	v_mov_b32_e32 v40, v0
	v_mov_b32_e32 v41, v0
	v_mov_b32_e32 v42, v0
	v_mov_b32_e32 v43, v0
	v_mov_b32_e32 v44, v0
	v_mov_b32_e32 v45, v0
	v_mov_b32_e32 v46, v0
	v_mov_b32_e32 v47, v0
	v_mov_b32_e32 v48, v0
	v_mov_b32_e32 v49, v0
	v_mov_b32_e32 v50, v0
	v_mov_b32_e32 v51, v0
	v_mov_b32_e32 v52, v0
	v_mov_b32_e32 v53, v0
	v_mov_b32_e32 v54, v0
	v_mov_b32_e32 v55, v0
	v_mov_b32_e32 v56, v0
	v_mov_b32_e32 v57, v0
	v_mov_b32_e32 v58, v0
	v_mov_b32_e32 v59, v0
	v_mov_b32_e32 v60, v0
	v_mov_b32_e32 v61, v0
	v_mov_b32_e32 v62, v0
	v_mov_b32_e32 v63, v0
	v_mov_b32_e32 v64, v0
	v_mov_b32_e32 v65, v0
	v_mov_b32_e32 v66, v0
	v_mov_b32_e32 v67, v0
	v_mov_b32_e32 v68, v0
	v_mov_b32_e32 v69, v0
	v_mov_b32_e32 v70, v0
	v_mov_b32_e32 v71, v0
	v_mov_b32_e32 v72, v0
	v_mov_b32_e32 v73, v0
	v_mov_b32_e32 v74, v0
	v_mov_b32_e32 v75, v0
	v_mov_b32_e32 v76, v0
	v_mov_b32_e32 v77, v0
	v_mov_b32_e32 v78, v0
	v_mov_b32_e32 v79, v0
	v_mov_b32_e32 v80, v0
	v_mov_b32_e32 v81, v0
	v_mov_b32_e32 v82, v0
	v_mov_b32_e32 v83, v0
	v_mov_b32_e32 v84, v0
	v_mov_b32_e32 v85, v0
	v_mov_b32_e32 v86, v0
	v_mov_b32_e32 v87, v0
	v_mov_b32_e32 v88, v0
	v_mov_b32_e32 v89, v0
	v_mov_b32_e32 v90, v0
	v_mov_b32_e32 v91, v0
	v_mov_b32_e32 v92, v0
	v_mov_b32_e32 v93, v0
	v_mov_b32_e32 v94, v0
	v_mov_b32_e32 v95, v0
	v_mov_b32_e32 v96, v0
	v_mov_b32_e32 v97, v0
	v_mov_b32_e32 v98, v0
	v_mov_b32_e32 v99, v0
	v_mov_b32_e32 v100, v0
	v_mov_b32_e32 v101, v0
	v_mov_b32_e32 v102, v0
	v_mov_b32_e32 v103, v0
	v_mov_b32_e32 v104, v0
	v_mov_b32_e32 v105, v0
	v_mov_b32_e32 v106, v0
	v_mov_b32_e32 v107, v0
	v_mov_b32_e32 v108, v0
	v_mov_b32_e32 v109, v0
	v_mov_b32_e32 v110, v0
	v_mov_b32_e32 v111, v0
	v_mov_b32_e32 v112, v0
	v_mov_b32_e32 v113, v0
	v_mov_b32_e32 v114, v0
	v_mov_b32_e32 v115, v0
	v_mov_b32_e32 v116, v0
	v_mov_b32_e32 v117, v0
	v_mov_b32_e32 v118, v0
	v_mov_b32_e32 v119, v0
	v_mov_b32_e32 v120, v0
	v_mov_b32_e32 v121, v0
	v_mov_b32_e32 v122, v0
	v_mov_b32_e32 v123, v0
	v_mov_b32_e32 v124, v0
	v_mov_b32_e32 v125, v0
	v_mov_b32_e32 v126, v0
	v_mov_b32_e32 v127, v0
	s_barrier
	s_add_u32 m0, s35, 0xc000
	s_nop 0
	global_load_lds_dwordx4 v128, s[76:77]
	s_add_u32 m0, s35, 0xe000
	s_nop 0
	global_load_lds_dwordx4 v130, s[76:77]
	s_add_u32 s76, s76, 0x80
	s_addc_u32 s77, s77, 0
.LBB0_187:
	ds_read_b128 v[176:179], v164
	ds_read_b128 v[180:183], v164 offset:1024
	ds_read_b128 v[184:187], v164 offset:2048
	ds_read_b128 v[188:191], v164 offset:3072
	ds_read_b128 v[192:195], v162
	ds_read_b128 v[196:199], v162 offset:1024
	ds_read_b128 v[200:203], v162 offset:2048
	ds_read_b128 v[204:207], v162 offset:3072
	ds_read_b128 v[208:211], v162 offset:4096
	ds_read_b128 v[212:215], v162 offset:5120
	ds_read_b128 v[216:219], v162 offset:6144
	ds_read_b128 v[220:223], v162 offset:7168
	s_waitcnt lgkmcnt(8)
	s_barrier
	s_waitcnt lgkmcnt(0)
	s_setprio 1
	v_mfma_f32_16x16x32_bf16 v[124:127], v[176:179], v[192:195], v[124:127]
	v_mfma_f32_16x16x32_bf16 v[120:123], v[184:187], v[192:195], v[120:123]
	v_mfma_f32_16x16x32_bf16 v[116:119], v[176:179], v[200:203], v[116:119]
	v_mfma_f32_16x16x32_bf16 v[112:115], v[184:187], v[200:203], v[112:115]
	v_mfma_f32_16x16x32_bf16 v[108:111], v[176:179], v[208:211], v[108:111]
	v_mfma_f32_16x16x32_bf16 v[104:107], v[184:187], v[208:211], v[104:107]
	v_mfma_f32_16x16x32_bf16 v[100:103], v[176:179], v[216:219], v[100:103]
	v_mfma_f32_16x16x32_bf16 v[96:99], v[184:187], v[216:219], v[96:99]
	v_mfma_f32_16x16x32_bf16 v[124:127], v[180:183], v[196:199], v[124:127]
	v_mfma_f32_16x16x32_bf16 v[120:123], v[188:191], v[196:199], v[120:123]
	v_mfma_f32_16x16x32_bf16 v[116:119], v[180:183], v[204:207], v[116:119]
	v_mfma_f32_16x16x32_bf16 v[112:115], v[188:191], v[204:207], v[112:115]
	v_mfma_f32_16x16x32_bf16 v[108:111], v[180:183], v[212:215], v[108:111]
	v_mfma_f32_16x16x32_bf16 v[104:107], v[188:191], v[212:215], v[104:107]
	v_mfma_f32_16x16x32_bf16 v[100:103], v[180:183], v[220:223], v[100:103]
	v_mfma_f32_16x16x32_bf16 v[96:99], v[188:191], v[220:223], v[96:99]
	s_setprio 0
	s_barrier
	s_add_u32 m0, s35, 0x10000
	ds_read_b128 v[224:227], v164 offset:16384
	ds_read_b128 v[228:231], v164 offset:17408
	ds_read_b128 v[232:235], v164 offset:18432
	ds_read_b128 v[236:239], v164 offset:19456
	global_load_lds_dwordx4 v128, s[42:43]
	s_add_u32 m0, s35, 0x12000
	s_nop 0
	global_load_lds_dwordx4 v130, s[42:43]
	s_add_u32 s42, s42, 0x80
	s_addc_u32 s43, s43, 0
	s_add_i32 s34, s34, 2
	s_barrier
	s_waitcnt lgkmcnt(0)
	s_setprio 1
	v_mfma_f32_16x16x32_bf16 v[92:95], v[224:227], v[192:195], v[92:95]
	v_mfma_f32_16x16x32_bf16 v[88:91], v[232:235], v[192:195], v[88:91]
	v_mfma_f32_16x16x32_bf16 v[84:87], v[224:227], v[200:203], v[84:87]
	v_mfma_f32_16x16x32_bf16 v[80:83], v[232:235], v[200:203], v[80:83]
	v_mfma_f32_16x16x32_bf16 v[76:79], v[224:227], v[208:211], v[76:79]
	v_mfma_f32_16x16x32_bf16 v[72:75], v[232:235], v[208:211], v[72:75]
	v_mfma_f32_16x16x32_bf16 v[68:71], v[224:227], v[216:219], v[68:71]
	v_mfma_f32_16x16x32_bf16 v[64:67], v[232:235], v[216:219], v[64:67]
	v_mfma_f32_16x16x32_bf16 v[92:95], v[228:231], v[196:199], v[92:95]
	v_mfma_f32_16x16x32_bf16 v[88:91], v[236:239], v[196:199], v[88:91]
	v_mfma_f32_16x16x32_bf16 v[84:87], v[228:231], v[204:207], v[84:87]
	v_mfma_f32_16x16x32_bf16 v[80:83], v[236:239], v[204:207], v[80:83]
	v_mfma_f32_16x16x32_bf16 v[76:79], v[228:231], v[212:215], v[76:79]
	v_mfma_f32_16x16x32_bf16 v[72:75], v[236:239], v[212:215], v[72:75]
	v_mfma_f32_16x16x32_bf16 v[68:71], v[228:231], v[220:223], v[68:71]
	v_mfma_f32_16x16x32_bf16 v[64:67], v[236:239], v[220:223], v[64:67]
	s_setprio 0
	s_barrier
	s_add_u32 m0, s35, 0x0
	ds_read_b128 v[192:195], v162 offset:16384
	ds_read_b128 v[196:199], v162 offset:17408
	ds_read_b128 v[200:203], v162 offset:18432
	ds_read_b128 v[204:207], v162 offset:19456
	ds_read_b128 v[208:211], v162 offset:20480
	ds_read_b128 v[212:215], v162 offset:21504
	ds_read_b128 v[216:219], v162 offset:22528
	ds_read_b128 v[220:223], v162 offset:23552
	global_load_lds_dwordx4 v128, s[72:73]
	s_add_u32 m0, s35, 0x2000
	s_nop 0
	global_load_lds_dwordx4 v130, s[72:73]
	s_add_u32 s72, s72, 0x80
	s_addc_u32 s73, s73, 0
	s_waitcnt lgkmcnt(0)
	s_barrier
	s_waitcnt lgkmcnt(0)
	s_setprio 1
	v_mfma_f32_16x16x32_bf16 v[60:63], v[176:179], v[192:195], v[60:63]
	v_mfma_f32_16x16x32_bf16 v[56:59], v[184:187], v[192:195], v[56:59]
	v_mfma_f32_16x16x32_bf16 v[52:55], v[176:179], v[200:203], v[52:55]
	v_mfma_f32_16x16x32_bf16 v[48:51], v[184:187], v[200:203], v[48:51]
	v_mfma_f32_16x16x32_bf16 v[44:47], v[176:179], v[208:211], v[44:47]
	v_mfma_f32_16x16x32_bf16 v[40:43], v[184:187], v[208:211], v[40:43]
	v_mfma_f32_16x16x32_bf16 v[36:39], v[176:179], v[216:219], v[36:39]
	v_mfma_f32_16x16x32_bf16 v[32:35], v[184:187], v[216:219], v[32:35]
	v_mfma_f32_16x16x32_bf16 v[60:63], v[180:183], v[196:199], v[60:63]
	v_mfma_f32_16x16x32_bf16 v[56:59], v[188:191], v[196:199], v[56:59]
	v_mfma_f32_16x16x32_bf16 v[52:55], v[180:183], v[204:207], v[52:55]
	v_mfma_f32_16x16x32_bf16 v[48:51], v[188:191], v[204:207], v[48:51]
	v_mfma_f32_16x16x32_bf16 v[44:47], v[180:183], v[212:215], v[44:47]
	v_mfma_f32_16x16x32_bf16 v[40:43], v[188:191], v[212:215], v[40:43]
	v_mfma_f32_16x16x32_bf16 v[36:39], v[180:183], v[220:223], v[36:39]
	v_mfma_f32_16x16x32_bf16 v[32:35], v[188:191], v[220:223], v[32:35]
	s_setprio 0
	s_barrier
	s_add_u32 m0, s35, 0x14000
	s_nop 0
	global_load_lds_dwordx4 v128, s[78:79]
	s_add_u32 m0, s35, 0x16000
	s_nop 0
	global_load_lds_dwordx4 v130, s[78:79]
	s_add_u32 s78, s78, 0x80
	s_addc_u32 s79, s79, 0
	s_add_u32 m0, s35, 0x4000
	s_nop 0
	global_load_lds_dwordx4 v128, s[76:77]
	s_add_u32 m0, s35, 0x6000
	s_nop 0
	global_load_lds_dwordx4 v130, s[76:77]
	s_add_u32 s76, s76, 0x80
	s_addc_u32 s77, s77, 0
	s_waitcnt vmcnt(8)
	s_barrier
	s_setprio 1
	v_mfma_f32_16x16x32_bf16 v[28:31], v[224:227], v[192:195], v[28:31]
	v_mfma_f32_16x16x32_bf16 v[24:27], v[232:235], v[192:195], v[24:27]
	v_mfma_f32_16x16x32_bf16 v[20:23], v[224:227], v[200:203], v[20:23]
	v_mfma_f32_16x16x32_bf16 v[16:19], v[232:235], v[200:203], v[16:19]
	v_mfma_f32_16x16x32_bf16 v[12:15], v[224:227], v[208:211], v[12:15]
	v_mfma_f32_16x16x32_bf16 v[8:11], v[232:235], v[208:211], v[8:11]
	v_mfma_f32_16x16x32_bf16 v[4:7], v[224:227], v[216:219], v[4:7]
	v_mfma_f32_16x16x32_bf16 v[0:3], v[232:235], v[216:219], v[0:3]
	v_mfma_f32_16x16x32_bf16 v[28:31], v[228:231], v[196:199], v[28:31]
	v_mfma_f32_16x16x32_bf16 v[24:27], v[236:239], v[196:199], v[24:27]
	v_mfma_f32_16x16x32_bf16 v[20:23], v[228:231], v[204:207], v[20:23]
	v_mfma_f32_16x16x32_bf16 v[16:19], v[236:239], v[204:207], v[16:19]
	v_mfma_f32_16x16x32_bf16 v[12:15], v[228:231], v[212:215], v[12:15]
	v_mfma_f32_16x16x32_bf16 v[8:11], v[236:239], v[212:215], v[8:11]
	v_mfma_f32_16x16x32_bf16 v[4:7], v[228:231], v[220:223], v[4:7]
	v_mfma_f32_16x16x32_bf16 v[0:3], v[236:239], v[220:223], v[0:3]
	s_setprio 0
	s_barrier
	ds_read_b128 v[176:179], v164 offset:32768
	ds_read_b128 v[180:183], v164 offset:33792
	ds_read_b128 v[184:187], v164 offset:34816
	ds_read_b128 v[188:191], v164 offset:35840
	ds_read_b128 v[192:195], v162 offset:32768
	ds_read_b128 v[196:199], v162 offset:33792
	ds_read_b128 v[200:203], v162 offset:34816
	ds_read_b128 v[204:207], v162 offset:35840
	ds_read_b128 v[208:211], v162 offset:36864
	ds_read_b128 v[212:215], v162 offset:37888
	ds_read_b128 v[216:219], v162 offset:38912
	ds_read_b128 v[220:223], v162 offset:39936
	s_waitcnt lgkmcnt(8)
	s_barrier
	s_waitcnt lgkmcnt(0)
	s_setprio 1
	v_mfma_f32_16x16x32_bf16 v[124:127], v[176:179], v[192:195], v[124:127]
	v_mfma_f32_16x16x32_bf16 v[120:123], v[184:187], v[192:195], v[120:123]
	v_mfma_f32_16x16x32_bf16 v[116:119], v[176:179], v[200:203], v[116:119]
	v_mfma_f32_16x16x32_bf16 v[112:115], v[184:187], v[200:203], v[112:115]
	v_mfma_f32_16x16x32_bf16 v[108:111], v[176:179], v[208:211], v[108:111]
	v_mfma_f32_16x16x32_bf16 v[104:107], v[184:187], v[208:211], v[104:107]
	v_mfma_f32_16x16x32_bf16 v[100:103], v[176:179], v[216:219], v[100:103]
	v_mfma_f32_16x16x32_bf16 v[96:99], v[184:187], v[216:219], v[96:99]
	v_mfma_f32_16x16x32_bf16 v[124:127], v[180:183], v[196:199], v[124:127]
	v_mfma_f32_16x16x32_bf16 v[120:123], v[188:191], v[196:199], v[120:123]
	v_mfma_f32_16x16x32_bf16 v[116:119], v[180:183], v[204:207], v[116:119]
	v_mfma_f32_16x16x32_bf16 v[112:115], v[188:191], v[204:207], v[112:115]
	v_mfma_f32_16x16x32_bf16 v[108:111], v[180:183], v[212:215], v[108:111]
	v_mfma_f32_16x16x32_bf16 v[104:107], v[188:191], v[212:215], v[104:107]
	v_mfma_f32_16x16x32_bf16 v[100:103], v[180:183], v[220:223], v[100:103]
	v_mfma_f32_16x16x32_bf16 v[96:99], v[188:191], v[220:223], v[96:99]
	s_setprio 0
	s_barrier
	s_add_u32 m0, s35, 0x18000
	ds_read_b128 v[224:227], v164 offset:49152
	ds_read_b128 v[228:231], v164 offset:50176
	ds_read_b128 v[232:235], v164 offset:51200
	ds_read_b128 v[236:239], v164 offset:52224
	global_load_lds_dwordx4 v128, s[42:43]
	s_add_u32 m0, s35, 0x1a000
	s_nop 0
	global_load_lds_dwordx4 v130, s[42:43]
	s_add_u32 s42, s42, 0x80
	s_addc_u32 s43, s43, 0
	s_barrier
	s_waitcnt lgkmcnt(0)
	s_setprio 1
	v_mfma_f32_16x16x32_bf16 v[92:95], v[224:227], v[192:195], v[92:95]
	v_mfma_f32_16x16x32_bf16 v[88:91], v[232:235], v[192:195], v[88:91]
	v_mfma_f32_16x16x32_bf16 v[84:87], v[224:227], v[200:203], v[84:87]
	v_mfma_f32_16x16x32_bf16 v[80:83], v[232:235], v[200:203], v[80:83]
	v_mfma_f32_16x16x32_bf16 v[76:79], v[224:227], v[208:211], v[76:79]
	v_mfma_f32_16x16x32_bf16 v[72:75], v[232:235], v[208:211], v[72:75]
	v_mfma_f32_16x16x32_bf16 v[68:71], v[224:227], v[216:219], v[68:71]
	v_mfma_f32_16x16x32_bf16 v[64:67], v[232:235], v[216:219], v[64:67]
	v_mfma_f32_16x16x32_bf16 v[92:95], v[228:231], v[196:199], v[92:95]
	v_mfma_f32_16x16x32_bf16 v[88:91], v[236:239], v[196:199], v[88:91]
	v_mfma_f32_16x16x32_bf16 v[84:87], v[228:231], v[204:207], v[84:87]
	v_mfma_f32_16x16x32_bf16 v[80:83], v[236:239], v[204:207], v[80:83]
	v_mfma_f32_16x16x32_bf16 v[76:79], v[228:231], v[212:215], v[76:79]
	v_mfma_f32_16x16x32_bf16 v[72:75], v[236:239], v[212:215], v[72:75]
	v_mfma_f32_16x16x32_bf16 v[68:71], v[228:231], v[220:223], v[68:71]
	v_mfma_f32_16x16x32_bf16 v[64:67], v[236:239], v[220:223], v[64:67]
	s_setprio 0
	s_barrier
	s_add_u32 m0, s35, 0x8000
	ds_read_b128 v[192:195], v162 offset:49152
	ds_read_b128 v[196:199], v162 offset:50176
	ds_read_b128 v[200:203], v162 offset:51200
	ds_read_b128 v[204:207], v162 offset:52224
	ds_read_b128 v[208:211], v162 offset:53248
	ds_read_b128 v[212:215], v162 offset:54272
	ds_read_b128 v[216:219], v162 offset:55296
	ds_read_b128 v[220:223], v162 offset:56320
	global_load_lds_dwordx4 v128, s[72:73]
	s_add_u32 m0, s35, 0xa000
	s_nop 0
	global_load_lds_dwordx4 v130, s[72:73]
	s_add_u32 s72, s72, 0x80
	s_addc_u32 s73, s73, 0
	s_waitcnt lgkmcnt(0)
	s_barrier
	s_waitcnt lgkmcnt(0)
	s_setprio 1
	v_mfma_f32_16x16x32_bf16 v[60:63], v[176:179], v[192:195], v[60:63]
	v_mfma_f32_16x16x32_bf16 v[56:59], v[184:187], v[192:195], v[56:59]
	v_mfma_f32_16x16x32_bf16 v[52:55], v[176:179], v[200:203], v[52:55]
	v_mfma_f32_16x16x32_bf16 v[48:51], v[184:187], v[200:203], v[48:51]
	v_mfma_f32_16x16x32_bf16 v[44:47], v[176:179], v[208:211], v[44:47]
	v_mfma_f32_16x16x32_bf16 v[40:43], v[184:187], v[208:211], v[40:43]
	v_mfma_f32_16x16x32_bf16 v[36:39], v[176:179], v[216:219], v[36:39]
	v_mfma_f32_16x16x32_bf16 v[32:35], v[184:187], v[216:219], v[32:35]
	v_mfma_f32_16x16x32_bf16 v[60:63], v[180:183], v[196:199], v[60:63]
	v_mfma_f32_16x16x32_bf16 v[56:59], v[188:191], v[196:199], v[56:59]
	v_mfma_f32_16x16x32_bf16 v[52:55], v[180:183], v[204:207], v[52:55]
	v_mfma_f32_16x16x32_bf16 v[48:51], v[188:191], v[204:207], v[48:51]
	v_mfma_f32_16x16x32_bf16 v[44:47], v[180:183], v[212:215], v[44:47]
	v_mfma_f32_16x16x32_bf16 v[40:43], v[188:191], v[212:215], v[40:43]
	v_mfma_f32_16x16x32_bf16 v[36:39], v[180:183], v[220:223], v[36:39]
	v_mfma_f32_16x16x32_bf16 v[32:35], v[188:191], v[220:223], v[32:35]
	s_setprio 0
	s_barrier
	s_add_u32 m0, s35, 0x1c000
	s_nop 0
	global_load_lds_dwordx4 v128, s[78:79]
	s_add_u32 m0, s35, 0x1e000
	s_nop 0
	global_load_lds_dwordx4 v130, s[78:79]
	s_add_u32 s78, s78, 0x80
	s_addc_u32 s79, s79, 0
	s_add_u32 m0, s35, 0xc000
	s_nop 0
	global_load_lds_dwordx4 v128, s[76:77]
	s_add_u32 m0, s35, 0xe000
	s_nop 0
	global_load_lds_dwordx4 v130, s[76:77]
	s_add_u32 s76, s76, 0x80
	s_addc_u32 s77, s77, 0
	s_waitcnt vmcnt(8)
	s_barrier
	s_setprio 1
	v_mfma_f32_16x16x32_bf16 v[28:31], v[224:227], v[192:195], v[28:31]
	v_mfma_f32_16x16x32_bf16 v[24:27], v[232:235], v[192:195], v[24:27]
	v_mfma_f32_16x16x32_bf16 v[20:23], v[224:227], v[200:203], v[20:23]
	v_mfma_f32_16x16x32_bf16 v[16:19], v[232:235], v[200:203], v[16:19]
	v_mfma_f32_16x16x32_bf16 v[12:15], v[224:227], v[208:211], v[12:15]
	v_mfma_f32_16x16x32_bf16 v[8:11], v[232:235], v[208:211], v[8:11]
	v_mfma_f32_16x16x32_bf16 v[4:7], v[224:227], v[216:219], v[4:7]
	v_mfma_f32_16x16x32_bf16 v[0:3], v[232:235], v[216:219], v[0:3]
	v_mfma_f32_16x16x32_bf16 v[28:31], v[228:231], v[196:199], v[28:31]
	v_mfma_f32_16x16x32_bf16 v[24:27], v[236:239], v[196:199], v[24:27]
	v_mfma_f32_16x16x32_bf16 v[20:23], v[228:231], v[204:207], v[20:23]
	v_mfma_f32_16x16x32_bf16 v[16:19], v[236:239], v[204:207], v[16:19]
	v_mfma_f32_16x16x32_bf16 v[12:15], v[228:231], v[212:215], v[12:15]
	v_mfma_f32_16x16x32_bf16 v[8:11], v[236:239], v[212:215], v[8:11]
	v_mfma_f32_16x16x32_bf16 v[4:7], v[228:231], v[220:223], v[4:7]
	v_mfma_f32_16x16x32_bf16 v[0:3], v[236:239], v[220:223], v[0:3]
	s_setprio 0
	s_cmp_lt_u32 s34, s3
	s_barrier
	s_cbranch_scc1 .LBB0_187
	s_mov_b64 s[72:73], 0x80
	s_mov_b64 s[76:77], 0x100
	s_mov_b64 s[78:79], 0x180
	s_add_i32 s66, s2, -1
	s_lshl_b64 s[2:3], s[66:67], 7
	s_add_u32 s2, s54, s2
	s_addc_u32 s3, s55, s3
	v_readfirstlane_b32 s34, v174
	v_lshl_add_u64 v[150:151], s[2:3], 0, v[128:129]
	s_mov_b32 m0, s34
	v_lshl_add_u64 v[130:131], s[2:3], 0, v[130:131]
	v_readfirstlane_b32 s2, v175
	ds_read_b128 v[132:135], v164
	ds_read_b128 v[136:139], v164 offset:1024
	ds_read_b128 v[140:143], v164 offset:2048
	ds_read_b128 v[144:147], v164 offset:3072
	ds_read_b128 v[158:161], v162
	ds_read_b128 v[166:169], v162 offset:1024
	ds_read_b128 v[170:173], v162 offset:2048
	ds_read_b128 v[176:179], v162 offset:3072
	ds_read_b128 v[180:183], v162 offset:4096
	ds_read_b128 v[184:187], v162 offset:5120
	ds_read_b128 v[188:191], v162 offset:6144
	ds_read_b128 v[192:195], v162 offset:7168
	global_load_lds_dwordx4 v[150:151], off
	s_mov_b32 m0, s2
	s_nop 0
	global_load_lds_dwordx4 v[130:131], off
	s_barrier
	s_waitcnt lgkmcnt(0)
	s_setprio 1
	s_waitcnt lgkmcnt(0)
	v_mfma_f32_16x16x32_bf16 v[124:127], v[132:135], v[158:161], v[124:127]
	v_mfma_f32_16x16x32_bf16 v[120:123], v[140:143], v[158:161], v[120:123]
	v_mfma_f32_16x16x32_bf16 v[116:119], v[132:135], v[170:173], v[116:119]
	v_mfma_f32_16x16x32_bf16 v[112:115], v[140:143], v[170:173], v[112:115]
	v_mfma_f32_16x16x32_bf16 v[100:103], v[132:135], v[188:191], v[100:103]
	v_mfma_f32_16x16x32_bf16 v[96:99], v[140:143], v[188:191], v[96:99]
	v_mfma_f32_16x16x32_bf16 v[124:127], v[136:139], v[166:169], v[124:127]
	v_mfma_f32_16x16x32_bf16 v[120:123], v[144:147], v[166:169], v[120:123]
	v_mfma_f32_16x16x32_bf16 v[116:119], v[136:139], v[176:179], v[116:119]
	v_mfma_f32_16x16x32_bf16 v[112:115], v[144:147], v[176:179], v[112:115]
	v_mfma_f32_16x16x32_bf16 v[108:111], v[132:135], v[180:183], v[108:111]
	v_mfma_f32_16x16x32_bf16 v[104:107], v[140:143], v[180:183], v[104:107]
	v_mfma_f32_16x16x32_bf16 v[100:103], v[136:139], v[192:195], v[100:103]
	v_mfma_f32_16x16x32_bf16 v[96:99], v[144:147], v[192:195], v[96:99]
	v_mfma_f32_16x16x32_bf16 v[196:199], v[136:139], v[184:187], v[108:111]
	v_mfma_f32_16x16x32_bf16 v[200:203], v[144:147], v[184:187], v[104:107]
	s_setprio 0
	s_barrier
	s_nop 1
	ds_read_b128 v[104:107], v164 offset:16384
	ds_read_b128 v[108:111], v164 offset:17408
	ds_read_b128 v[204:207], v164 offset:18432
	ds_read_b128 v[208:211], v164 offset:19456
	s_barrier
	s_waitcnt lgkmcnt(0)
	s_setprio 1
	s_waitcnt lgkmcnt(0)
	v_mfma_f32_16x16x32_bf16 v[84:87], v[104:107], v[170:173], v[84:87]
	v_mfma_f32_16x16x32_bf16 v[80:83], v[204:207], v[170:173], v[80:83]
	v_mfma_f32_16x16x32_bf16 v[68:71], v[104:107], v[188:191], v[68:71]
	v_mfma_f32_16x16x32_bf16 v[64:67], v[204:207], v[188:191], v[64:67]
	v_mfma_f32_16x16x32_bf16 v[92:95], v[104:107], v[158:161], v[92:95]
	v_mfma_f32_16x16x32_bf16 v[88:91], v[204:207], v[158:161], v[88:91]
	v_mfma_f32_16x16x32_bf16 v[84:87], v[108:111], v[176:179], v[84:87]
	v_mfma_f32_16x16x32_bf16 v[80:83], v[208:211], v[176:179], v[80:83]
	v_mfma_f32_16x16x32_bf16 v[76:79], v[104:107], v[180:183], v[76:79]
	v_mfma_f32_16x16x32_bf16 v[72:75], v[204:207], v[180:183], v[72:75]
	v_mfma_f32_16x16x32_bf16 v[68:71], v[108:111], v[192:195], v[68:71]
	v_mfma_f32_16x16x32_bf16 v[64:67], v[208:211], v[192:195], v[64:67]
	v_mfma_f32_16x16x32_bf16 v[212:215], v[108:111], v[166:169], v[92:95]
	v_mfma_f32_16x16x32_bf16 v[158:161], v[208:211], v[166:169], v[88:91]
	v_mfma_f32_16x16x32_bf16 v[166:169], v[108:111], v[184:187], v[76:79]
	v_mfma_f32_16x16x32_bf16 v[170:173], v[208:211], v[184:187], v[72:75]
	s_setprio 0
	s_barrier
	s_nop 0
	ds_read_b128 v[72:75], v162 offset:16384
	ds_read_b128 v[76:79], v162 offset:17408
	ds_read_b128 v[88:91], v162 offset:18432
	ds_read_b128 v[92:95], v162 offset:19456
	ds_read_b128 v[174:177], v162 offset:20480
	ds_read_b128 v[178:181], v162 offset:21504
	ds_read_b128 v[182:185], v162 offset:22528
	ds_read_b128 v[186:189], v162 offset:23552
	s_waitcnt vmcnt(4)
	s_barrier
	s_waitcnt lgkmcnt(0)
	s_setprio 1
	s_waitcnt lgkmcnt(0)
	v_mfma_f32_16x16x32_bf16 v[60:63], v[132:135], v[72:75], v[60:63]
	v_mfma_f32_16x16x32_bf16 v[56:59], v[140:143], v[72:75], v[56:59]
	v_mfma_f32_16x16x32_bf16 v[52:55], v[132:135], v[88:91], v[52:55]
	v_mfma_f32_16x16x32_bf16 v[48:51], v[140:143], v[88:91], v[48:51]
	v_mfma_f32_16x16x32_bf16 v[36:39], v[132:135], v[182:185], v[36:39]
	v_mfma_f32_16x16x32_bf16 v[32:35], v[140:143], v[182:185], v[32:35]
	v_mfma_f32_16x16x32_bf16 v[60:63], v[136:139], v[76:79], v[60:63]
	v_mfma_f32_16x16x32_bf16 v[56:59], v[144:147], v[76:79], v[56:59]
	v_mfma_f32_16x16x32_bf16 v[52:55], v[136:139], v[92:95], v[52:55]
	v_mfma_f32_16x16x32_bf16 v[48:51], v[144:147], v[92:95], v[48:51]
	v_mfma_f32_16x16x32_bf16 v[44:47], v[132:135], v[174:177], v[44:47]
	v_mfma_f32_16x16x32_bf16 v[40:43], v[140:143], v[174:177], v[40:43]
	v_mfma_f32_16x16x32_bf16 v[36:39], v[136:139], v[186:189], v[36:39]
	v_mfma_f32_16x16x32_bf16 v[32:35], v[144:147], v[186:189], v[32:35]
	v_mfma_f32_16x16x32_bf16 v[190:193], v[136:139], v[178:181], v[44:47]
	v_mfma_f32_16x16x32_bf16 v[216:219], v[144:147], v[178:181], v[40:43]
	s_setprio 0
	s_setprio 1
	v_mfma_f32_16x16x32_bf16 v[20:23], v[104:107], v[88:91], v[20:23]
	v_mfma_f32_16x16x32_bf16 v[16:19], v[204:207], v[88:91], v[16:19]
	v_mfma_f32_16x16x32_bf16 v[4:7], v[104:107], v[182:185], v[4:7]
	v_mfma_f32_16x16x32_bf16 v[0:3], v[204:207], v[182:185], v[0:3]
	v_mfma_f32_16x16x32_bf16 v[28:31], v[104:107], v[72:75], v[28:31]
	v_mfma_f32_16x16x32_bf16 v[24:27], v[204:207], v[72:75], v[24:27]
	v_mfma_f32_16x16x32_bf16 v[20:23], v[108:111], v[92:95], v[20:23]
	v_mfma_f32_16x16x32_bf16 v[16:19], v[208:211], v[92:95], v[16:19]
	v_mfma_f32_16x16x32_bf16 v[12:15], v[104:107], v[174:177], v[12:15]
	v_mfma_f32_16x16x32_bf16 v[8:11], v[204:207], v[174:177], v[8:11]
	v_mfma_f32_16x16x32_bf16 v[4:7], v[108:111], v[186:189], v[4:7]
	v_mfma_f32_16x16x32_bf16 v[0:3], v[208:211], v[186:189], v[0:3]
	v_mfma_f32_16x16x32_bf16 v[130:133], v[108:111], v[76:79], v[28:31]
	v_mfma_f32_16x16x32_bf16 v[134:137], v[208:211], v[76:79], v[24:27]
	v_mfma_f32_16x16x32_bf16 v[138:141], v[108:111], v[178:181], v[12:15]
	v_mfma_f32_16x16x32_bf16 v[142:145], v[208:211], v[178:181], v[8:11]
	s_setprio 0
	s_barrier
	s_nop 0
	ds_read_b128 v[8:11], v164 offset:32768
	ds_read_b128 v[12:15], v164 offset:33792
	ds_read_b128 v[174:177], v164 offset:34816
	ds_read_b128 v[178:181], v164 offset:35840
	ds_read_b128 v[24:27], v162 offset:32768
	ds_read_b128 v[28:31], v162 offset:33792
	ds_read_b128 v[40:43], v162 offset:34816
	ds_read_b128 v[44:47], v162 offset:35840
	ds_read_b128 v[182:185], v162 offset:36864
	ds_read_b128 v[186:189], v162 offset:37888
	ds_read_b128 v[204:207], v162 offset:38912
	ds_read_b128 v[208:211], v162 offset:39936
	s_waitcnt vmcnt(2)
	s_barrier
	s_waitcnt lgkmcnt(0)
	s_setprio 1
	s_waitcnt lgkmcnt(0)
	v_mfma_f32_16x16x32_bf16 v[72:75], v[8:11], v[24:27], v[124:127]
	v_mfma_f32_16x16x32_bf16 v[124:127], v[12:15], v[28:31], v[72:75]
	v_mfma_f32_16x16x32_bf16 v[72:75], v[174:177], v[24:27], v[120:123]
	v_mfma_f32_16x16x32_bf16 v[120:123], v[178:181], v[28:31], v[72:75]
	v_mfma_f32_16x16x32_bf16 v[72:75], v[8:11], v[40:43], v[116:119]
	v_mfma_f32_16x16x32_bf16 v[108:111], v[12:15], v[44:47], v[72:75]
	v_mfma_f32_16x16x32_bf16 v[72:75], v[174:177], v[40:43], v[112:115]
	v_mfma_f32_16x16x32_bf16 v[104:107], v[178:181], v[44:47], v[72:75]
	v_mfma_f32_16x16x32_bf16 v[72:75], v[8:11], v[182:185], v[196:199]
	v_mfma_f32_16x16x32_bf16 v[92:95], v[12:15], v[186:189], v[72:75]
	v_mfma_f32_16x16x32_bf16 v[72:75], v[174:177], v[182:185], v[200:203]
	v_mfma_f32_16x16x32_bf16 v[88:91], v[178:181], v[186:189], v[72:75]
	v_mfma_f32_16x16x32_bf16 v[72:75], v[8:11], v[204:207], v[100:103]
	v_mfma_f32_16x16x32_bf16 v[76:79], v[12:15], v[208:211], v[72:75]
	v_mfma_f32_16x16x32_bf16 v[72:75], v[174:177], v[204:207], v[96:99]
	v_mfma_f32_16x16x32_bf16 v[72:75], v[178:181], v[208:211], v[72:75]
	s_setprio 0
	s_barrier
	ds_read_b128 v[194:197], v164 offset:49152
	ds_read_b128 v[198:201], v164 offset:50176
	ds_read_b128 v[220:223], v164 offset:51200
	ds_read_b128 v[224:227], v164 offset:52224
	s_waitcnt vmcnt(0)
	s_barrier
	s_waitcnt lgkmcnt(0)
	s_setprio 1
	s_waitcnt lgkmcnt(0)
	v_mfma_f32_16x16x32_bf16 v[96:99], v[194:197], v[24:27], v[212:215]
	v_mfma_f32_16x16x32_bf16 v[24:27], v[220:223], v[24:27], v[158:161]
	v_mfma_f32_16x16x32_bf16 v[112:115], v[224:227], v[28:31], v[24:27]
	v_mfma_f32_16x16x32_bf16 v[24:27], v[194:197], v[40:43], v[84:87]
	v_mfma_f32_16x16x32_bf16 v[100:103], v[198:201], v[44:47], v[24:27]
	v_mfma_f32_16x16x32_bf16 v[24:27], v[220:223], v[40:43], v[80:83]
	v_mfma_f32_16x16x32_bf16 v[116:119], v[198:201], v[28:31], v[96:99]
	v_mfma_f32_16x16x32_bf16 v[96:99], v[224:227], v[44:47], v[24:27]
	v_mfma_f32_16x16x32_bf16 v[24:27], v[194:197], v[182:185], v[166:169]
	v_mfma_f32_16x16x32_bf16 v[84:87], v[198:201], v[186:189], v[24:27]
	v_mfma_f32_16x16x32_bf16 v[24:27], v[220:223], v[182:185], v[170:173]
	v_mfma_f32_16x16x32_bf16 v[80:83], v[224:227], v[186:189], v[24:27]
	v_mfma_f32_16x16x32_bf16 v[24:27], v[194:197], v[204:207], v[68:71]
	v_mfma_f32_16x16x32_bf16 v[68:71], v[198:201], v[208:211], v[24:27]
	v_mfma_f32_16x16x32_bf16 v[24:27], v[220:223], v[204:207], v[64:67]
	v_mfma_f32_16x16x32_bf16 v[64:67], v[224:227], v[208:211], v[24:27]
	s_setprio 0
	s_barrier
	ds_read_b128 v[158:161], v162 offset:49152
	ds_read_b128 v[164:167], v162 offset:50176
	ds_read_b128 v[168:171], v162 offset:51200
	ds_read_b128 v[182:185], v162 offset:52224
	ds_read_b128 v[186:189], v162 offset:53248
	ds_read_b128 v[202:205], v162 offset:54272
	ds_read_b128 v[206:209], v162 offset:55296
	ds_read_b128 v[210:213], v162 offset:56320
	s_barrier
	s_waitcnt lgkmcnt(0)
	s_setprio 1
	s_waitcnt lgkmcnt(0)
	v_mfma_f32_16x16x32_bf16 v[24:27], v[8:11], v[158:161], v[60:63]
	v_mfma_f32_16x16x32_bf16 v[60:63], v[12:15], v[164:167], v[24:27]
	v_mfma_f32_16x16x32_bf16 v[24:27], v[174:177], v[158:161], v[56:59]
	v_mfma_f32_16x16x32_bf16 v[56:59], v[178:181], v[164:167], v[24:27]
	v_mfma_f32_16x16x32_bf16 v[24:27], v[8:11], v[168:171], v[52:55]
	v_mfma_f32_16x16x32_bf16 v[44:47], v[12:15], v[182:185], v[24:27]
	v_mfma_f32_16x16x32_bf16 v[24:27], v[174:177], v[168:171], v[48:51]
	v_mfma_f32_16x16x32_bf16 v[40:43], v[178:181], v[182:185], v[24:27]
	v_mfma_f32_16x16x32_bf16 v[24:27], v[8:11], v[186:189], v[190:193]
	v_mfma_f32_16x16x32_bf16 v[8:11], v[8:11], v[206:209], v[36:39]
	v_mfma_f32_16x16x32_bf16 v[28:31], v[12:15], v[202:205], v[24:27]
	v_mfma_f32_16x16x32_bf16 v[24:27], v[174:177], v[186:189], v[216:219]
	v_mfma_f32_16x16x32_bf16 v[12:15], v[12:15], v[210:213], v[8:11]
	v_mfma_f32_16x16x32_bf16 v[8:11], v[174:177], v[206:209], v[32:35]
	v_mfma_f32_16x16x32_bf16 v[24:27], v[178:181], v[202:205], v[24:27]
	v_mfma_f32_16x16x32_bf16 v[8:11], v[178:181], v[210:213], v[8:11]
	s_setprio 0
	s_setprio 1
	v_mfma_f32_16x16x32_bf16 v[32:35], v[194:197], v[158:161], v[130:133]
	v_mfma_f32_16x16x32_bf16 v[52:55], v[198:201], v[164:167], v[32:35]
	v_mfma_f32_16x16x32_bf16 v[32:35], v[220:223], v[158:161], v[134:137]
	v_mfma_f32_16x16x32_bf16 v[16:19], v[220:223], v[168:171], v[16:19]
	v_mfma_f32_16x16x32_bf16 v[48:51], v[224:227], v[164:167], v[32:35]
	v_mfma_f32_16x16x32_bf16 v[20:23], v[194:197], v[168:171], v[20:23]
	v_mfma_f32_16x16x32_bf16 v[32:35], v[224:227], v[182:185], v[16:19]
	v_mfma_f32_16x16x32_bf16 v[16:19], v[194:197], v[186:189], v[138:141]
	v_mfma_f32_16x16x32_bf16 v[36:39], v[198:201], v[182:185], v[20:23]
	v_mfma_f32_16x16x32_bf16 v[20:23], v[198:201], v[202:205], v[16:19]
	v_mfma_f32_16x16x32_bf16 v[16:19], v[220:223], v[186:189], v[142:145]
	v_mfma_f32_16x16x32_bf16 v[4:7], v[194:197], v[206:209], v[4:7]
	v_mfma_f32_16x16x32_bf16 v[0:3], v[220:223], v[206:209], v[0:3]
	v_mfma_f32_16x16x32_bf16 v[16:19], v[224:227], v[202:205], v[16:19]
	v_mfma_f32_16x16x32_bf16 v[4:7], v[198:201], v[210:213], v[4:7]
	v_mfma_f32_16x16x32_bf16 v[0:3], v[224:227], v[210:213], v[0:3]
	s_setprio 0
	s_movk_i32 s2, 0x100
	v_cmp_gt_u32_e32 vcc, s2, v157
	s_barrier
	s_and_saveexec_b64 s[2:3], vcc
	s_cbranch_execz .LBB0_190
	s_barrier
